# Down-GEMM residual epilogue with full-line accesses: accumulator fragments transposed across lanes (ds_bpermute) so each global load/store covers 8 rows x 128 B instead of 16 rows x four 16-B pieces
# speedup vs baseline: 1.0423x; 1.0423x over previous
;   DI void operator()(const pg8::f32x4 (&acc)[2][2][4][2], const pg8::Unit& u, int wr, int wc, int fr, int fq) const {
;     const int row0 = u.pm * 256 + wr * 64 + fr, col0 = u.pn * 256 + wc * 32 + 8 * fq;
;     const int b = (u.pm * 256) / TT;
; #pragma unroll
;     for (int ai = 0; ai < 2; ++ai)
; #pragma unroll
;       for (int m = 0; m < 4; ++m) {
;         const int row = row0 + ai * 128 + m * 16;
;         const int t = row - b * TT;
;         const bool isc = t >= TL;
;         float* dst = isc ? xc + ((size_t)b * TC + (t - TL)) * DM : xout + ((size_t)b * TL + t) * DM;
;         const float* src = src_input ? (isc ? cin + ((size_t)b * TC + (t - TL)) * DM : xin + ((size_t)b * TL + t) * DM) : dst;
;         const float* gate = modl + (size_t)(isc ? 16 : b) * 6144 + gi * DM;
; #pragma unroll
;         for (int bj = 0; bj < 2; ++bj) {
;           const int col = col0 + bj * 128;
; #pragma unroll
;           for (int n = 0; n < 2; ++n) {
;             pg8::f32x4 sv = *(const pg8::f32x4*)(src + col + 4 * n);
;             pg8::f32x4 gv = *(const pg8::f32x4*)(gate + col + 4 * n);
;             pg8::f32x4 o = sv + gv * acc[ai][bj][m][n];
;             *(pg8::f32x4*)(dst + col + 4 * n) = o;
;           }
;         }
;       }
;   }
.LBB0_1507:
	s_mov_b32 s4, 0x38e38e39
	v_mul_hi_i32 v142, v148, s4
	v_lshrrev_b32_e32 v144, 31, v142
	v_ashrrev_i32_e32 v142, 1, v142
	v_add_u32_e32 v142, v142, v144
	s_movk_i32 s4, 0xf700
	s_load_dwordx4 s[24:27], s[0:1], 0x100
	v_lshlrev_b32_e32 v143, 8, v148
	v_mul_lo_u32 v144, v142, s4
	v_add_u32_e32 v143, v144, v143
	v_add_u32_e32 v160, v143, v154
	v_ashrrev_i32_e32 v143, 31, v142
	v_readlane_b32 s4, v252, 14
	s_movk_i32 s21, 0x7ff
	v_lshlrev_b64 v[144:145], 23, v[142:143]
	v_lshlrev_b64 v[146:147], 20, v[142:143]
	v_ashrrev_i32_e32 v143, 31, v160
	v_add_u32_e32 v148, 0xfffff800, v160
	v_readlane_b32 s5, v252, 15
	v_cmp_lt_i32_e32 vcc, s21, v160
	v_lshl_or_b32 v150, v149, 8, v156
	s_waitcnt lgkmcnt(0)
	v_lshl_add_u64 v[144:145], s[24:25], 0, v[144:145]
	v_lshl_add_u64 v[146:147], s[4:5], 0, v[146:147]
	v_cndmask_b32_e64 v149, v143, 0, vcc
	v_cndmask_b32_e32 v148, v160, v148, vcc
	v_cndmask_b32_e32 v163, v145, v147, vcc
	v_cndmask_b32_e32 v162, v144, v146, vcc
	v_lshlrev_b64 v[148:149], 12, v[148:149]
	v_lshl_add_u64 v[162:163], v[162:163], 0, v[148:149]
	v_cndmask_b32_e64 v143, v142, 16, vcc
	v_mov_b64_e32 v[148:149], s[10:11]
	s_movk_i32 s22, 0x6000
	v_ashrrev_i32_e32 v151, 31, v150
	v_mad_i64_i32 v[164:165], s[4:5], v143, s22, v[148:149]
	v_lshlrev_b64 v[150:151], 2, v[150:151]
	v_lshl_add_u64 v[176:177], v[164:165], 0, v[150:151]
	v_lshl_add_u64 v[174:175], v[162:163], 0, v[150:151]
	s_mov_b32 s4, 0xaaaaaaaa
	s_mov_b32 s5, 0xaaaaaaaa
	s_mov_b64 s[24:25], 0x10000
	s_mov_b64 s[26:27], 0x50000
	v_and_b32_e32 v166, 63, v182
	v_lshrrev_b32_e32 v167, 3, v166
	v_and_b32_e32 v168, 7, v166
	v_lshrrev_b32_e32 v210, 1, v168
	v_lshl_add_u32 v210, v210, 4, v167
	v_lshlrev_b32_e32 v210, 2, v210
	v_add_u32_e32 v211, 32, v210
	v_lshrrev_b32_e32 v169, 4, v166
	v_and_b32_e32 v170, 15, v166
	v_lshlrev_b32_e32 v171, 4, v168
	v_lshlrev_b32_e32 v169, 5, v169
	v_sub_u32_e32 v171, v171, v169
	v_sub_u32_e32 v172, v167, v170
	v_lshl_add_u32 v172, v172, 12, v171
	v_ashrrev_i32_e32 v173, 31, v172
	v_ashrrev_i32_e32 v170, 31, v171
	v_add_co_u32_e32 v212, vcc, v174, v172
	s_nop 1
	v_addc_co_u32_e32 v213, vcc, v175, v173, vcc
	v_lshl_add_u64 v[214:215], v[212:213], 0, s[24:25]
	v_add_co_u32_e32 v214, vcc, 0xffff8000, v214
	s_nop 1
	v_addc_co_u32_e32 v215, vcc, -1, v215, vcc
	v_mov_b32_e32 v150, v212
	v_mov_b32_e32 v151, v213
	v_mov_b32_e32 v192, v214
	v_mov_b32_e32 v193, v215
	v_add_co_u32_e32 v176, vcc, v176, v171
	s_nop 1
	v_addc_co_u32_e32 v177, vcc, v177, v170, vcc
	global_load_dwordx4 v[202:205], v[176:177], off
	global_load_dwordx4 v[206:209], v[176:177], off offset:512
	global_load_dwordx4 v[216:219], v[212:213], off
	global_load_dwordx4 v[220:223], v[214:215], off
	global_load_dwordx4 v[224:227], v[212:213], off offset:512
	global_load_dwordx4 v[228:231], v[214:215], off offset:512
	v_lshl_add_u64 v[212:213], v[212:213], 0, s[24:25]
	v_lshl_add_u64 v[214:215], v[214:215], 0, s[24:25]
	global_load_dwordx4 v[232:235], v[212:213], off
	global_load_dwordx4 v[236:239], v[214:215], off
	global_load_dwordx4 v[240:243], v[212:213], off offset:512
	global_load_dwordx4 v[244:247], v[214:215], off offset:512
	s_waitcnt vmcnt(4)
	ds_bpermute_b32 v142, v210, v124
	ds_bpermute_b32 v146, v210, v120
	ds_bpermute_b32 v143, v210, v125
	ds_bpermute_b32 v147, v210, v121
	ds_bpermute_b32 v144, v210, v126
	ds_bpermute_b32 v148, v210, v122
	ds_bpermute_b32 v145, v210, v127
	ds_bpermute_b32 v149, v210, v123
	s_waitcnt lgkmcnt(0)
	v_cndmask_b32_e64 v162, v142, v146, s[4:5]
	v_cndmask_b32_e64 v163, v143, v147, s[4:5]
	v_cndmask_b32_e64 v164, v144, v148, s[4:5]
	v_cndmask_b32_e64 v165, v145, v149, s[4:5]
	v_pk_fma_f32 v[218:219], v[164:165], v[204:205], v[218:219]
	v_pk_fma_f32 v[216:217], v[162:163], v[202:203], v[216:217]
	global_store_dwordx4 v[150:151], v[216:219], off
	ds_bpermute_b32 v142, v211, v124
	ds_bpermute_b32 v146, v211, v120
	ds_bpermute_b32 v143, v211, v125
	ds_bpermute_b32 v147, v211, v121
	ds_bpermute_b32 v144, v211, v126
	ds_bpermute_b32 v148, v211, v122
	ds_bpermute_b32 v145, v211, v127
	ds_bpermute_b32 v149, v211, v123
	s_waitcnt lgkmcnt(0)
	v_cndmask_b32_e64 v162, v142, v146, s[4:5]
	v_cndmask_b32_e64 v163, v143, v147, s[4:5]
	v_cndmask_b32_e64 v164, v144, v148, s[4:5]
	v_cndmask_b32_e64 v165, v145, v149, s[4:5]
	v_pk_fma_f32 v[222:223], v[164:165], v[204:205], v[222:223]
	v_pk_fma_f32 v[220:221], v[162:163], v[202:203], v[220:221]
	global_store_dwordx4 v[192:193], v[220:223], off
	ds_bpermute_b32 v142, v210, v116
	ds_bpermute_b32 v146, v210, v104
	ds_bpermute_b32 v143, v210, v117
	ds_bpermute_b32 v147, v210, v105
	ds_bpermute_b32 v144, v210, v118
	ds_bpermute_b32 v148, v210, v106
	ds_bpermute_b32 v145, v210, v119
	ds_bpermute_b32 v149, v210, v107
	s_waitcnt lgkmcnt(0)
	v_cndmask_b32_e64 v162, v142, v146, s[4:5]
	v_cndmask_b32_e64 v163, v143, v147, s[4:5]
	v_cndmask_b32_e64 v164, v144, v148, s[4:5]
	v_cndmask_b32_e64 v165, v145, v149, s[4:5]
	v_pk_fma_f32 v[226:227], v[164:165], v[208:209], v[226:227]
	v_pk_fma_f32 v[224:225], v[162:163], v[206:207], v[224:225]
	global_store_dwordx4 v[150:151], v[224:227], off offset:512
	ds_bpermute_b32 v142, v211, v116
	ds_bpermute_b32 v146, v211, v104
	ds_bpermute_b32 v143, v211, v117
	ds_bpermute_b32 v147, v211, v105
	ds_bpermute_b32 v144, v211, v118
	ds_bpermute_b32 v148, v211, v106
	ds_bpermute_b32 v145, v211, v119
	ds_bpermute_b32 v149, v211, v107
	s_waitcnt lgkmcnt(0)
;   DI void operator()(const pg8::f32x4 (&acc)[2][2][4][2], const pg8::Unit& u, int wr, int wc, int fr, int fq) const {
;     const int row0 = u.pm * 256 + wr * 64 + fr, col0 = u.pn * 256 + wc * 32 + 8 * fq;
;     const int b = (u.pm * 256) / TT;
; #pragma unroll
;     for (int ai = 0; ai < 2; ++ai)
; #pragma unroll
;       for (int m = 0; m < 4; ++m) {
;         const int row = row0 + ai * 128 + m * 16;
;         const int t = row - b * TT;
;         const bool isc = t >= TL;
;         float* dst = isc ? xc + ((size_t)b * TC + (t - TL)) * DM : xout + ((size_t)b * TL + t) * DM;
;         const float* src = src_input ? (isc ? cin + ((size_t)b * TC + (t - TL)) * DM : xin + ((size_t)b * TL + t) * DM) : dst;
;         const float* gate = modl + (size_t)(isc ? 16 : b) * 6144 + gi * DM;
; #pragma unroll
;         for (int bj = 0; bj < 2; ++bj) {
;           const int col = col0 + bj * 128;
; #pragma unroll
;           for (int n = 0; n < 2; ++n) {
;             pg8::f32x4 sv = *(const pg8::f32x4*)(src + col + 4 * n);
;             pg8::f32x4 gv = *(const pg8::f32x4*)(gate + col + 4 * n);
;             pg8::f32x4 o = sv + gv * acc[ai][bj][m][n];
;             *(pg8::f32x4*)(dst + col + 4 * n) = o;
;           }
;         }
;       }
;   }
	v_cndmask_b32_e64 v162, v142, v146, s[4:5]
	v_cndmask_b32_e64 v163, v143, v147, s[4:5]
	v_cndmask_b32_e64 v164, v144, v148, s[4:5]
	v_cndmask_b32_e64 v165, v145, v149, s[4:5]
	v_pk_fma_f32 v[230:231], v[164:165], v[208:209], v[230:231]
	v_pk_fma_f32 v[228:229], v[162:163], v[206:207], v[228:229]
	global_store_dwordx4 v[192:193], v[228:231], off offset:512
	v_lshl_add_u64 v[212:213], v[212:213], 0, s[24:25]
	v_lshl_add_u64 v[214:215], v[214:215], 0, s[24:25]
	global_load_dwordx4 v[216:219], v[212:213], off
	global_load_dwordx4 v[220:223], v[214:215], off
	global_load_dwordx4 v[224:227], v[212:213], off offset:512
	global_load_dwordx4 v[228:231], v[214:215], off offset:512
	s_waitcnt vmcnt(8)
	v_lshl_add_u64 v[150:151], v[150:151], 0, s[24:25]
	v_lshl_add_u64 v[192:193], v[192:193], 0, s[24:25]
	ds_bpermute_b32 v142, v210, v112
	ds_bpermute_b32 v146, v210, v108
	ds_bpermute_b32 v143, v210, v113
	ds_bpermute_b32 v147, v210, v109
	ds_bpermute_b32 v144, v210, v114
	ds_bpermute_b32 v148, v210, v110
	ds_bpermute_b32 v145, v210, v115
	ds_bpermute_b32 v149, v210, v111
	s_waitcnt lgkmcnt(0)
	v_cndmask_b32_e64 v162, v142, v146, s[4:5]
	v_cndmask_b32_e64 v163, v143, v147, s[4:5]
	v_cndmask_b32_e64 v164, v144, v148, s[4:5]
	v_cndmask_b32_e64 v165, v145, v149, s[4:5]
	v_pk_fma_f32 v[234:235], v[164:165], v[204:205], v[234:235]
	v_pk_fma_f32 v[232:233], v[162:163], v[202:203], v[232:233]
	global_store_dwordx4 v[150:151], v[232:235], off
	ds_bpermute_b32 v142, v211, v112
	ds_bpermute_b32 v146, v211, v108
	ds_bpermute_b32 v143, v211, v113
	ds_bpermute_b32 v147, v211, v109
	ds_bpermute_b32 v144, v211, v114
	ds_bpermute_b32 v148, v211, v110
	ds_bpermute_b32 v145, v211, v115
	ds_bpermute_b32 v149, v211, v111
	s_waitcnt lgkmcnt(0)
	v_cndmask_b32_e64 v162, v142, v146, s[4:5]
	v_cndmask_b32_e64 v163, v143, v147, s[4:5]
	v_cndmask_b32_e64 v164, v144, v148, s[4:5]
	v_cndmask_b32_e64 v165, v145, v149, s[4:5]
	v_pk_fma_f32 v[238:239], v[164:165], v[204:205], v[238:239]
	v_pk_fma_f32 v[236:237], v[162:163], v[202:203], v[236:237]
	global_store_dwordx4 v[192:193], v[236:239], off
	ds_bpermute_b32 v142, v210, v100
	ds_bpermute_b32 v146, v210, v88
	ds_bpermute_b32 v143, v210, v101
	ds_bpermute_b32 v147, v210, v89
	ds_bpermute_b32 v144, v210, v102
	ds_bpermute_b32 v148, v210, v90
	ds_bpermute_b32 v145, v210, v103
	ds_bpermute_b32 v149, v210, v91
	s_waitcnt lgkmcnt(0)
	v_cndmask_b32_e64 v162, v142, v146, s[4:5]
	v_cndmask_b32_e64 v163, v143, v147, s[4:5]
	v_cndmask_b32_e64 v164, v144, v148, s[4:5]
	v_cndmask_b32_e64 v165, v145, v149, s[4:5]
	v_pk_fma_f32 v[242:243], v[164:165], v[208:209], v[242:243]
	v_pk_fma_f32 v[240:241], v[162:163], v[206:207], v[240:241]
	global_store_dwordx4 v[150:151], v[240:243], off offset:512
	ds_bpermute_b32 v142, v211, v100
	ds_bpermute_b32 v146, v211, v88
	ds_bpermute_b32 v143, v211, v101
	ds_bpermute_b32 v147, v211, v89
	ds_bpermute_b32 v144, v211, v102
	ds_bpermute_b32 v148, v211, v90
	ds_bpermute_b32 v145, v211, v103
	ds_bpermute_b32 v149, v211, v91
	s_waitcnt lgkmcnt(0)
	v_cndmask_b32_e64 v162, v142, v146, s[4:5]
	v_cndmask_b32_e64 v163, v143, v147, s[4:5]
	v_cndmask_b32_e64 v164, v144, v148, s[4:5]
	v_cndmask_b32_e64 v165, v145, v149, s[4:5]
	v_pk_fma_f32 v[246:247], v[164:165], v[208:209], v[246:247]
	v_pk_fma_f32 v[244:245], v[162:163], v[206:207], v[244:245]
	global_store_dwordx4 v[192:193], v[244:247], off offset:512
	v_lshl_add_u64 v[212:213], v[212:213], 0, s[24:25]
	v_lshl_add_u64 v[214:215], v[214:215], 0, s[24:25]
	global_load_dwordx4 v[232:235], v[212:213], off
	global_load_dwordx4 v[236:239], v[214:215], off
	global_load_dwordx4 v[240:243], v[212:213], off offset:512
	global_load_dwordx4 v[244:247], v[214:215], off offset:512
	s_waitcnt vmcnt(8)
	v_lshl_add_u64 v[150:151], v[150:151], 0, s[24:25]
	v_lshl_add_u64 v[192:193], v[192:193], 0, s[24:25]
	ds_bpermute_b32 v142, v210, v96
	ds_bpermute_b32 v146, v210, v92
	ds_bpermute_b32 v143, v210, v97
	ds_bpermute_b32 v147, v210, v93
	ds_bpermute_b32 v144, v210, v98
	ds_bpermute_b32 v148, v210, v94
	ds_bpermute_b32 v145, v210, v99
	ds_bpermute_b32 v149, v210, v95
	s_waitcnt lgkmcnt(0)
	v_cndmask_b32_e64 v162, v142, v146, s[4:5]
	v_cndmask_b32_e64 v163, v143, v147, s[4:5]
	v_cndmask_b32_e64 v164, v144, v148, s[4:5]
	v_cndmask_b32_e64 v165, v145, v149, s[4:5]
	v_pk_fma_f32 v[218:219], v[164:165], v[204:205], v[218:219]
	v_pk_fma_f32 v[216:217], v[162:163], v[202:203], v[216:217]
	global_store_dwordx4 v[150:151], v[216:219], off
	ds_bpermute_b32 v142, v211, v96
	ds_bpermute_b32 v146, v211, v92
	ds_bpermute_b32 v143, v211, v97
	ds_bpermute_b32 v147, v211, v93
	ds_bpermute_b32 v144, v211, v98
	ds_bpermute_b32 v148, v211, v94
	ds_bpermute_b32 v145, v211, v99
	ds_bpermute_b32 v149, v211, v95
	s_waitcnt lgkmcnt(0)
	v_cndmask_b32_e64 v162, v142, v146, s[4:5]
	v_cndmask_b32_e64 v163, v143, v147, s[4:5]
	v_cndmask_b32_e64 v164, v144, v148, s[4:5]
	v_cndmask_b32_e64 v165, v145, v149, s[4:5]
	v_pk_fma_f32 v[222:223], v[164:165], v[204:205], v[222:223]
	v_pk_fma_f32 v[220:221], v[162:163], v[202:203], v[220:221]
	global_store_dwordx4 v[192:193], v[220:223], off
	ds_bpermute_b32 v142, v210, v84
	ds_bpermute_b32 v146, v210, v72
	ds_bpermute_b32 v143, v210, v85
	ds_bpermute_b32 v147, v210, v73
	ds_bpermute_b32 v144, v210, v86
	ds_bpermute_b32 v148, v210, v74
	ds_bpermute_b32 v145, v210, v87
	ds_bpermute_b32 v149, v210, v75
	s_waitcnt lgkmcnt(0)
;   DI void operator()(const pg8::f32x4 (&acc)[2][2][4][2], const pg8::Unit& u, int wr, int wc, int fr, int fq) const {
;     const int row0 = u.pm * 256 + wr * 64 + fr, col0 = u.pn * 256 + wc * 32 + 8 * fq;
;     const int b = (u.pm * 256) / TT;
; #pragma unroll
;     for (int ai = 0; ai < 2; ++ai)
; #pragma unroll
;       for (int m = 0; m < 4; ++m) {
;         const int row = row0 + ai * 128 + m * 16;
;         const int t = row - b * TT;
;         const bool isc = t >= TL;
;         float* dst = isc ? xc + ((size_t)b * TC + (t - TL)) * DM : xout + ((size_t)b * TL + t) * DM;
;         const float* src = src_input ? (isc ? cin + ((size_t)b * TC + (t - TL)) * DM : xin + ((size_t)b * TL + t) * DM) : dst;
;         const float* gate = modl + (size_t)(isc ? 16 : b) * 6144 + gi * DM;
; #pragma unroll
;         for (int bj = 0; bj < 2; ++bj) {
;           const int col = col0 + bj * 128;
; #pragma unroll
;           for (int n = 0; n < 2; ++n) {
;             pg8::f32x4 sv = *(const pg8::f32x4*)(src + col + 4 * n);
;             pg8::f32x4 gv = *(const pg8::f32x4*)(gate + col + 4 * n);
;             pg8::f32x4 o = sv + gv * acc[ai][bj][m][n];
;             *(pg8::f32x4*)(dst + col + 4 * n) = o;
;           }
;         }
;       }
;   }
	v_cndmask_b32_e64 v162, v142, v146, s[4:5]
	v_cndmask_b32_e64 v163, v143, v147, s[4:5]
	v_cndmask_b32_e64 v164, v144, v148, s[4:5]
	v_cndmask_b32_e64 v165, v145, v149, s[4:5]
	v_pk_fma_f32 v[226:227], v[164:165], v[208:209], v[226:227]
	v_pk_fma_f32 v[224:225], v[162:163], v[206:207], v[224:225]
	global_store_dwordx4 v[150:151], v[224:227], off offset:512
	ds_bpermute_b32 v142, v211, v84
	ds_bpermute_b32 v146, v211, v72
	ds_bpermute_b32 v143, v211, v85
	ds_bpermute_b32 v147, v211, v73
	ds_bpermute_b32 v144, v211, v86
	ds_bpermute_b32 v148, v211, v74
	ds_bpermute_b32 v145, v211, v87
	ds_bpermute_b32 v149, v211, v75
	s_waitcnt lgkmcnt(0)
	v_cndmask_b32_e64 v162, v142, v146, s[4:5]
	v_cndmask_b32_e64 v163, v143, v147, s[4:5]
	v_cndmask_b32_e64 v164, v144, v148, s[4:5]
	v_cndmask_b32_e64 v165, v145, v149, s[4:5]
	v_pk_fma_f32 v[230:231], v[164:165], v[208:209], v[230:231]
	v_pk_fma_f32 v[228:229], v[162:163], v[206:207], v[228:229]
	global_store_dwordx4 v[192:193], v[228:231], off offset:512
	v_lshl_add_u64 v[212:213], v[212:213], 0, s[26:27]
	v_lshl_add_u64 v[214:215], v[214:215], 0, s[26:27]
	global_load_dwordx4 v[216:219], v[212:213], off
	global_load_dwordx4 v[220:223], v[214:215], off
	global_load_dwordx4 v[224:227], v[212:213], off offset:512
	global_load_dwordx4 v[228:231], v[214:215], off offset:512
	s_waitcnt vmcnt(8)
	v_lshl_add_u64 v[150:151], v[150:151], 0, s[24:25]
	v_lshl_add_u64 v[192:193], v[192:193], 0, s[24:25]
	ds_bpermute_b32 v142, v210, v80
	ds_bpermute_b32 v146, v210, v76
	ds_bpermute_b32 v143, v210, v81
	ds_bpermute_b32 v147, v210, v77
	ds_bpermute_b32 v144, v210, v82
	ds_bpermute_b32 v148, v210, v78
	ds_bpermute_b32 v145, v210, v83
	ds_bpermute_b32 v149, v210, v79
	s_waitcnt lgkmcnt(0)
	v_cndmask_b32_e64 v162, v142, v146, s[4:5]
	v_cndmask_b32_e64 v163, v143, v147, s[4:5]
	v_cndmask_b32_e64 v164, v144, v148, s[4:5]
	v_cndmask_b32_e64 v165, v145, v149, s[4:5]
	v_pk_fma_f32 v[234:235], v[164:165], v[204:205], v[234:235]
	v_pk_fma_f32 v[232:233], v[162:163], v[202:203], v[232:233]
	global_store_dwordx4 v[150:151], v[232:235], off
	ds_bpermute_b32 v142, v211, v80
	ds_bpermute_b32 v146, v211, v76
	ds_bpermute_b32 v143, v211, v81
	ds_bpermute_b32 v147, v211, v77
	ds_bpermute_b32 v144, v211, v82
	ds_bpermute_b32 v148, v211, v78
	ds_bpermute_b32 v145, v211, v83
	ds_bpermute_b32 v149, v211, v79
	s_waitcnt lgkmcnt(0)
	v_cndmask_b32_e64 v162, v142, v146, s[4:5]
	v_cndmask_b32_e64 v163, v143, v147, s[4:5]
	v_cndmask_b32_e64 v164, v144, v148, s[4:5]
	v_cndmask_b32_e64 v165, v145, v149, s[4:5]
	v_pk_fma_f32 v[238:239], v[164:165], v[204:205], v[238:239]
	v_pk_fma_f32 v[236:237], v[162:163], v[202:203], v[236:237]
	global_store_dwordx4 v[192:193], v[236:239], off
	ds_bpermute_b32 v142, v210, v68
	ds_bpermute_b32 v146, v210, v64
	ds_bpermute_b32 v143, v210, v69
	ds_bpermute_b32 v147, v210, v65
	ds_bpermute_b32 v144, v210, v70
	ds_bpermute_b32 v148, v210, v66
	ds_bpermute_b32 v145, v210, v71
	ds_bpermute_b32 v149, v210, v67
	s_waitcnt lgkmcnt(0)
	v_cndmask_b32_e64 v162, v142, v146, s[4:5]
	v_cndmask_b32_e64 v163, v143, v147, s[4:5]
	v_cndmask_b32_e64 v164, v144, v148, s[4:5]
	v_cndmask_b32_e64 v165, v145, v149, s[4:5]
	v_pk_fma_f32 v[242:243], v[164:165], v[208:209], v[242:243]
	v_pk_fma_f32 v[240:241], v[162:163], v[206:207], v[240:241]
	global_store_dwordx4 v[150:151], v[240:243], off offset:512
	ds_bpermute_b32 v142, v211, v68
	ds_bpermute_b32 v146, v211, v64
	ds_bpermute_b32 v143, v211, v69
	ds_bpermute_b32 v147, v211, v65
	ds_bpermute_b32 v144, v211, v70
	ds_bpermute_b32 v148, v211, v66
	ds_bpermute_b32 v145, v211, v71
	ds_bpermute_b32 v149, v211, v67
	s_waitcnt lgkmcnt(0)
	v_cndmask_b32_e64 v162, v142, v146, s[4:5]
	v_cndmask_b32_e64 v163, v143, v147, s[4:5]
	v_cndmask_b32_e64 v164, v144, v148, s[4:5]
	v_cndmask_b32_e64 v165, v145, v149, s[4:5]
	v_pk_fma_f32 v[246:247], v[164:165], v[208:209], v[246:247]
	v_pk_fma_f32 v[244:245], v[162:163], v[206:207], v[244:245]
	global_store_dwordx4 v[192:193], v[244:247], off offset:512
	v_lshl_add_u64 v[212:213], v[212:213], 0, s[24:25]
	v_lshl_add_u64 v[214:215], v[214:215], 0, s[24:25]
	global_load_dwordx4 v[232:235], v[212:213], off
	global_load_dwordx4 v[236:239], v[214:215], off
	global_load_dwordx4 v[240:243], v[212:213], off offset:512
	global_load_dwordx4 v[244:247], v[214:215], off offset:512
	s_waitcnt vmcnt(8)
	v_lshl_add_u64 v[150:151], v[150:151], 0, s[26:27]
	v_lshl_add_u64 v[192:193], v[192:193], 0, s[26:27]
	ds_bpermute_b32 v142, v210, v60
	ds_bpermute_b32 v146, v210, v56
	ds_bpermute_b32 v143, v210, v61
	ds_bpermute_b32 v147, v210, v57
	ds_bpermute_b32 v144, v210, v62
	ds_bpermute_b32 v148, v210, v58
	ds_bpermute_b32 v145, v210, v63
	ds_bpermute_b32 v149, v210, v59
	s_waitcnt lgkmcnt(0)
	v_cndmask_b32_e64 v162, v142, v146, s[4:5]
	v_cndmask_b32_e64 v163, v143, v147, s[4:5]
	v_cndmask_b32_e64 v164, v144, v148, s[4:5]
	v_cndmask_b32_e64 v165, v145, v149, s[4:5]
	v_pk_fma_f32 v[218:219], v[164:165], v[204:205], v[218:219]
	v_pk_fma_f32 v[216:217], v[162:163], v[202:203], v[216:217]
	global_store_dwordx4 v[150:151], v[216:219], off
	ds_bpermute_b32 v142, v211, v60
	ds_bpermute_b32 v146, v211, v56
	ds_bpermute_b32 v143, v211, v61
	ds_bpermute_b32 v147, v211, v57
	ds_bpermute_b32 v144, v211, v62
	ds_bpermute_b32 v148, v211, v58
	ds_bpermute_b32 v145, v211, v63
	ds_bpermute_b32 v149, v211, v59
	s_waitcnt lgkmcnt(0)
;   DI void operator()(const pg8::f32x4 (&acc)[2][2][4][2], const pg8::Unit& u, int wr, int wc, int fr, int fq) const {
;     const int row0 = u.pm * 256 + wr * 64 + fr, col0 = u.pn * 256 + wc * 32 + 8 * fq;
;     const int b = (u.pm * 256) / TT;
; #pragma unroll
;     for (int ai = 0; ai < 2; ++ai)
; #pragma unroll
;       for (int m = 0; m < 4; ++m) {
;         const int row = row0 + ai * 128 + m * 16;
;         const int t = row - b * TT;
;         const bool isc = t >= TL;
;         float* dst = isc ? xc + ((size_t)b * TC + (t - TL)) * DM : xout + ((size_t)b * TL + t) * DM;
;         const float* src = src_input ? (isc ? cin + ((size_t)b * TC + (t - TL)) * DM : xin + ((size_t)b * TL + t) * DM) : dst;
;         const float* gate = modl + (size_t)(isc ? 16 : b) * 6144 + gi * DM;
; #pragma unroll
;         for (int bj = 0; bj < 2; ++bj) {
;           const int col = col0 + bj * 128;
; #pragma unroll
;           for (int n = 0; n < 2; ++n) {
;             pg8::f32x4 sv = *(const pg8::f32x4*)(src + col + 4 * n);
;             pg8::f32x4 gv = *(const pg8::f32x4*)(gate + col + 4 * n);
;             pg8::f32x4 o = sv + gv * acc[ai][bj][m][n];
;             *(pg8::f32x4*)(dst + col + 4 * n) = o;
;           }
;         }
;       }
;   }
	v_cndmask_b32_e64 v162, v142, v146, s[4:5]
	v_cndmask_b32_e64 v163, v143, v147, s[4:5]
	v_cndmask_b32_e64 v164, v144, v148, s[4:5]
	v_cndmask_b32_e64 v165, v145, v149, s[4:5]
	v_pk_fma_f32 v[222:223], v[164:165], v[204:205], v[222:223]
	v_pk_fma_f32 v[220:221], v[162:163], v[202:203], v[220:221]
	global_store_dwordx4 v[192:193], v[220:223], off
	ds_bpermute_b32 v142, v210, v52
	ds_bpermute_b32 v146, v210, v40
	ds_bpermute_b32 v143, v210, v53
	ds_bpermute_b32 v147, v210, v41
	ds_bpermute_b32 v144, v210, v54
	ds_bpermute_b32 v148, v210, v42
	ds_bpermute_b32 v145, v210, v55
	ds_bpermute_b32 v149, v210, v43
	s_waitcnt lgkmcnt(0)
	v_cndmask_b32_e64 v162, v142, v146, s[4:5]
	v_cndmask_b32_e64 v163, v143, v147, s[4:5]
	v_cndmask_b32_e64 v164, v144, v148, s[4:5]
	v_cndmask_b32_e64 v165, v145, v149, s[4:5]
	v_pk_fma_f32 v[226:227], v[164:165], v[208:209], v[226:227]
	v_pk_fma_f32 v[224:225], v[162:163], v[206:207], v[224:225]
	global_store_dwordx4 v[150:151], v[224:227], off offset:512
	ds_bpermute_b32 v142, v211, v52
	ds_bpermute_b32 v146, v211, v40
	ds_bpermute_b32 v143, v211, v53
	ds_bpermute_b32 v147, v211, v41
	ds_bpermute_b32 v144, v211, v54
	ds_bpermute_b32 v148, v211, v42
	ds_bpermute_b32 v145, v211, v55
	ds_bpermute_b32 v149, v211, v43
	s_waitcnt lgkmcnt(0)
	v_cndmask_b32_e64 v162, v142, v146, s[4:5]
	v_cndmask_b32_e64 v163, v143, v147, s[4:5]
	v_cndmask_b32_e64 v164, v144, v148, s[4:5]
	v_cndmask_b32_e64 v165, v145, v149, s[4:5]
	v_pk_fma_f32 v[230:231], v[164:165], v[208:209], v[230:231]
	v_pk_fma_f32 v[228:229], v[162:163], v[206:207], v[228:229]
	global_store_dwordx4 v[192:193], v[228:231], off offset:512
	v_lshl_add_u64 v[212:213], v[212:213], 0, s[24:25]
	v_lshl_add_u64 v[214:215], v[214:215], 0, s[24:25]
	global_load_dwordx4 v[216:219], v[212:213], off
	global_load_dwordx4 v[220:223], v[214:215], off
	global_load_dwordx4 v[224:227], v[212:213], off offset:512
	global_load_dwordx4 v[228:231], v[214:215], off offset:512
	s_waitcnt vmcnt(8)
	v_lshl_add_u64 v[150:151], v[150:151], 0, s[24:25]
	v_lshl_add_u64 v[192:193], v[192:193], 0, s[24:25]
	ds_bpermute_b32 v142, v210, v48
	ds_bpermute_b32 v146, v210, v44
	ds_bpermute_b32 v143, v210, v49
	ds_bpermute_b32 v147, v210, v45
	ds_bpermute_b32 v144, v210, v50
	ds_bpermute_b32 v148, v210, v46
	ds_bpermute_b32 v145, v210, v51
	ds_bpermute_b32 v149, v210, v47
	s_waitcnt lgkmcnt(0)
	v_cndmask_b32_e64 v162, v142, v146, s[4:5]
	v_cndmask_b32_e64 v163, v143, v147, s[4:5]
	v_cndmask_b32_e64 v164, v144, v148, s[4:5]
	v_cndmask_b32_e64 v165, v145, v149, s[4:5]
	v_pk_fma_f32 v[234:235], v[164:165], v[204:205], v[234:235]
	v_pk_fma_f32 v[232:233], v[162:163], v[202:203], v[232:233]
	global_store_dwordx4 v[150:151], v[232:235], off
	ds_bpermute_b32 v142, v211, v48
	ds_bpermute_b32 v146, v211, v44
	ds_bpermute_b32 v143, v211, v49
	ds_bpermute_b32 v147, v211, v45
	ds_bpermute_b32 v144, v211, v50
	ds_bpermute_b32 v148, v211, v46
	ds_bpermute_b32 v145, v211, v51
	ds_bpermute_b32 v149, v211, v47
	s_waitcnt lgkmcnt(0)
	v_cndmask_b32_e64 v162, v142, v146, s[4:5]
	v_cndmask_b32_e64 v163, v143, v147, s[4:5]
	v_cndmask_b32_e64 v164, v144, v148, s[4:5]
	v_cndmask_b32_e64 v165, v145, v149, s[4:5]
	v_pk_fma_f32 v[238:239], v[164:165], v[204:205], v[238:239]
	v_pk_fma_f32 v[236:237], v[162:163], v[202:203], v[236:237]
	global_store_dwordx4 v[192:193], v[236:239], off
	ds_bpermute_b32 v142, v210, v36
	ds_bpermute_b32 v146, v210, v24
	ds_bpermute_b32 v143, v210, v37
	ds_bpermute_b32 v147, v210, v25
	ds_bpermute_b32 v144, v210, v38
	ds_bpermute_b32 v148, v210, v26
	ds_bpermute_b32 v145, v210, v39
	ds_bpermute_b32 v149, v210, v27
	s_waitcnt lgkmcnt(0)
	v_cndmask_b32_e64 v162, v142, v146, s[4:5]
	v_cndmask_b32_e64 v163, v143, v147, s[4:5]
	v_cndmask_b32_e64 v164, v144, v148, s[4:5]
	v_cndmask_b32_e64 v165, v145, v149, s[4:5]
	v_pk_fma_f32 v[242:243], v[164:165], v[208:209], v[242:243]
	v_pk_fma_f32 v[240:241], v[162:163], v[206:207], v[240:241]
	global_store_dwordx4 v[150:151], v[240:243], off offset:512
	ds_bpermute_b32 v142, v211, v36
	ds_bpermute_b32 v146, v211, v24
	ds_bpermute_b32 v143, v211, v37
	ds_bpermute_b32 v147, v211, v25
	ds_bpermute_b32 v144, v211, v38
	ds_bpermute_b32 v148, v211, v26
	ds_bpermute_b32 v145, v211, v39
	ds_bpermute_b32 v149, v211, v27
	s_waitcnt lgkmcnt(0)
	v_cndmask_b32_e64 v162, v142, v146, s[4:5]
	v_cndmask_b32_e64 v163, v143, v147, s[4:5]
	v_cndmask_b32_e64 v164, v144, v148, s[4:5]
	v_cndmask_b32_e64 v165, v145, v149, s[4:5]
	v_pk_fma_f32 v[246:247], v[164:165], v[208:209], v[246:247]
	v_pk_fma_f32 v[244:245], v[162:163], v[206:207], v[244:245]
	global_store_dwordx4 v[192:193], v[244:247], off offset:512
	v_lshl_add_u64 v[212:213], v[212:213], 0, s[24:25]
	v_lshl_add_u64 v[214:215], v[214:215], 0, s[24:25]
	global_load_dwordx4 v[232:235], v[212:213], off
	global_load_dwordx4 v[236:239], v[214:215], off
	global_load_dwordx4 v[240:243], v[212:213], off offset:512
	global_load_dwordx4 v[244:247], v[214:215], off offset:512
	s_waitcnt vmcnt(8)
	v_lshl_add_u64 v[150:151], v[150:151], 0, s[24:25]
	v_lshl_add_u64 v[192:193], v[192:193], 0, s[24:25]
	ds_bpermute_b32 v142, v210, v32
	ds_bpermute_b32 v146, v210, v28
	ds_bpermute_b32 v143, v210, v33
	ds_bpermute_b32 v147, v210, v29
	ds_bpermute_b32 v144, v210, v34
	ds_bpermute_b32 v148, v210, v30
	ds_bpermute_b32 v145, v210, v35
	ds_bpermute_b32 v149, v210, v31
	s_waitcnt lgkmcnt(0)
; #define PG8_BAR __builtin_amdgcn_s_barrier()
; template <class Epi, class Sched, bool ALIGN_EPI = false, bool SP2 = false>
; __device__ __forceinline__ void gemm_phase(PG8_LAS unsigned char* lds, const Gemm g, const Sched& S, const Epi& E) {
;     ...
;         if constexpr (!Epi::AFTER_DRAIN) { E(acc, cur, wr, wc, fr, fq); S.done(cur); }
;         if (!has_next) break;
; #pragma unroll
;         for (int a = 0; a < 2; ++a)
; #pragma unroll
;             for (int b = 0; b < 2; ++b)
; #pragma unroll
;                 for (int m = 0; m < 4; ++m)
; #pragma unroll
;                     for (int n = 0; n < 2; ++n) acc[a][b][m][n] = (f32x4){0.f, 0.f, 0.f, 0.f};
;         cur = nxt; cA = nA; cB = nB; ++ui;
;         if constexpr (ALIGN_EPI) { if (wr == 1) PG8_BAR; }
;     }
;   DI void operator()(const pg8::f32x4 (&acc)[2][2][4][2], const pg8::Unit& u, int wr, int wc, int fr, int fq) const {
;     const int row0 = u.pm * 256 + wr * 64 + fr, col0 = u.pn * 256 + wc * 32 + 8 * fq;
;     const int b = (u.pm * 256) / TT;
; #pragma unroll
;     for (int ai = 0; ai < 2; ++ai)
; #pragma unroll
;       for (int m = 0; m < 4; ++m) {
;         const int row = row0 + ai * 128 + m * 16;
;         const int t = row - b * TT;
;         const bool isc = t >= TL;
;         float* dst = isc ? xc + ((size_t)b * TC + (t - TL)) * DM : xout + ((size_t)b * TL + t) * DM;
;         const float* src = src_input ? (isc ? cin + ((size_t)b * TC + (t - TL)) * DM : xin + ((size_t)b * TL + t) * DM) : dst;
;         const float* gate = modl + (size_t)(isc ? 16 : b) * 6144 + gi * DM;
; #pragma unroll
;         for (int bj = 0; bj < 2; ++bj) {
;           const int col = col0 + bj * 128;
; #pragma unroll
;           for (int n = 0; n < 2; ++n) {
;             pg8::f32x4 sv = *(const pg8::f32x4*)(src + col + 4 * n);
;             pg8::f32x4 gv = *(const pg8::f32x4*)(gate + col + 4 * n);
;             pg8::f32x4 o = sv + gv * acc[ai][bj][m][n];
;             *(pg8::f32x4*)(dst + col + 4 * n) = o;
;           }
;         }
;       }
;   }
	v_cndmask_b32_e64 v162, v142, v146, s[4:5]
	v_cndmask_b32_e64 v163, v143, v147, s[4:5]
	v_cndmask_b32_e64 v164, v144, v148, s[4:5]
	v_cndmask_b32_e64 v165, v145, v149, s[4:5]
	v_pk_fma_f32 v[218:219], v[164:165], v[204:205], v[218:219]
	v_pk_fma_f32 v[216:217], v[162:163], v[202:203], v[216:217]
	global_store_dwordx4 v[150:151], v[216:219], off
	ds_bpermute_b32 v142, v211, v32
	ds_bpermute_b32 v146, v211, v28
	ds_bpermute_b32 v143, v211, v33
	ds_bpermute_b32 v147, v211, v29
	ds_bpermute_b32 v144, v211, v34
	ds_bpermute_b32 v148, v211, v30
	ds_bpermute_b32 v145, v211, v35
	ds_bpermute_b32 v149, v211, v31
	s_waitcnt lgkmcnt(0)
	v_cndmask_b32_e64 v162, v142, v146, s[4:5]
	v_cndmask_b32_e64 v163, v143, v147, s[4:5]
	v_cndmask_b32_e64 v164, v144, v148, s[4:5]
	v_cndmask_b32_e64 v165, v145, v149, s[4:5]
	v_pk_fma_f32 v[222:223], v[164:165], v[204:205], v[222:223]
	v_pk_fma_f32 v[220:221], v[162:163], v[202:203], v[220:221]
	global_store_dwordx4 v[192:193], v[220:223], off
	ds_bpermute_b32 v142, v210, v20
	ds_bpermute_b32 v146, v210, v8
	ds_bpermute_b32 v143, v210, v21
	ds_bpermute_b32 v147, v210, v9
	ds_bpermute_b32 v144, v210, v22
	ds_bpermute_b32 v148, v210, v10
	ds_bpermute_b32 v145, v210, v23
	ds_bpermute_b32 v149, v210, v11
	s_waitcnt lgkmcnt(0)
	v_cndmask_b32_e64 v162, v142, v146, s[4:5]
	v_cndmask_b32_e64 v163, v143, v147, s[4:5]
	v_cndmask_b32_e64 v164, v144, v148, s[4:5]
	v_cndmask_b32_e64 v165, v145, v149, s[4:5]
	v_pk_fma_f32 v[226:227], v[164:165], v[208:209], v[226:227]
	v_pk_fma_f32 v[224:225], v[162:163], v[206:207], v[224:225]
	global_store_dwordx4 v[150:151], v[224:227], off offset:512
	ds_bpermute_b32 v142, v211, v20
	ds_bpermute_b32 v146, v211, v8
	ds_bpermute_b32 v143, v211, v21
	ds_bpermute_b32 v147, v211, v9
	ds_bpermute_b32 v144, v211, v22
	ds_bpermute_b32 v148, v211, v10
	ds_bpermute_b32 v145, v211, v23
	ds_bpermute_b32 v149, v211, v11
	s_waitcnt lgkmcnt(0)
	v_cndmask_b32_e64 v162, v142, v146, s[4:5]
	v_cndmask_b32_e64 v163, v143, v147, s[4:5]
	v_cndmask_b32_e64 v164, v144, v148, s[4:5]
	v_cndmask_b32_e64 v165, v145, v149, s[4:5]
	v_pk_fma_f32 v[230:231], v[164:165], v[208:209], v[230:231]
	v_pk_fma_f32 v[228:229], v[162:163], v[206:207], v[228:229]
	global_store_dwordx4 v[192:193], v[228:231], off offset:512
	s_waitcnt vmcnt(4)
	v_lshl_add_u64 v[150:151], v[150:151], 0, s[24:25]
	v_lshl_add_u64 v[192:193], v[192:193], 0, s[24:25]
	ds_bpermute_b32 v142, v210, v16
	ds_bpermute_b32 v146, v210, v12
	ds_bpermute_b32 v143, v210, v17
	ds_bpermute_b32 v147, v210, v13
	ds_bpermute_b32 v144, v210, v18
	ds_bpermute_b32 v148, v210, v14
	ds_bpermute_b32 v145, v210, v19
	ds_bpermute_b32 v149, v210, v15
	s_waitcnt lgkmcnt(0)
	v_cndmask_b32_e64 v162, v142, v146, s[4:5]
	v_cndmask_b32_e64 v163, v143, v147, s[4:5]
	v_cndmask_b32_e64 v164, v144, v148, s[4:5]
	v_cndmask_b32_e64 v165, v145, v149, s[4:5]
	v_pk_fma_f32 v[234:235], v[164:165], v[204:205], v[234:235]
	v_pk_fma_f32 v[232:233], v[162:163], v[202:203], v[232:233]
	global_store_dwordx4 v[150:151], v[232:235], off
	ds_bpermute_b32 v142, v211, v16
	ds_bpermute_b32 v146, v211, v12
	ds_bpermute_b32 v143, v211, v17
	ds_bpermute_b32 v147, v211, v13
	ds_bpermute_b32 v144, v211, v18
	ds_bpermute_b32 v148, v211, v14
	ds_bpermute_b32 v145, v211, v19
	ds_bpermute_b32 v149, v211, v15
	s_waitcnt lgkmcnt(0)
	v_cndmask_b32_e64 v162, v142, v146, s[4:5]
	v_cndmask_b32_e64 v163, v143, v147, s[4:5]
	v_cndmask_b32_e64 v164, v144, v148, s[4:5]
	v_cndmask_b32_e64 v165, v145, v149, s[4:5]
	v_pk_fma_f32 v[238:239], v[164:165], v[204:205], v[238:239]
	v_pk_fma_f32 v[236:237], v[162:163], v[202:203], v[236:237]
	global_store_dwordx4 v[192:193], v[236:239], off
	ds_bpermute_b32 v142, v210, v4
	ds_bpermute_b32 v146, v210, v0
	ds_bpermute_b32 v143, v210, v5
	ds_bpermute_b32 v147, v210, v1
	ds_bpermute_b32 v144, v210, v6
	ds_bpermute_b32 v148, v210, v2
	ds_bpermute_b32 v145, v210, v7
	ds_bpermute_b32 v149, v210, v3
	s_waitcnt lgkmcnt(0)
	v_cndmask_b32_e64 v162, v142, v146, s[4:5]
	v_cndmask_b32_e64 v163, v143, v147, s[4:5]
	v_cndmask_b32_e64 v164, v144, v148, s[4:5]
	v_cndmask_b32_e64 v165, v145, v149, s[4:5]
	v_pk_fma_f32 v[242:243], v[164:165], v[208:209], v[242:243]
	v_pk_fma_f32 v[240:241], v[162:163], v[206:207], v[240:241]
	global_store_dwordx4 v[150:151], v[240:243], off offset:512
	ds_bpermute_b32 v142, v211, v4
	ds_bpermute_b32 v146, v211, v0
	ds_bpermute_b32 v143, v211, v5
	ds_bpermute_b32 v147, v211, v1
	ds_bpermute_b32 v144, v211, v6
	ds_bpermute_b32 v148, v211, v2
	ds_bpermute_b32 v145, v211, v7
	ds_bpermute_b32 v149, v211, v3
	s_waitcnt lgkmcnt(0)
	v_cndmask_b32_e64 v162, v142, v146, s[4:5]
	v_cndmask_b32_e64 v163, v143, v147, s[4:5]
	v_cndmask_b32_e64 v164, v144, v148, s[4:5]
	v_cndmask_b32_e64 v165, v145, v149, s[4:5]
	v_pk_fma_f32 v[246:247], v[164:165], v[208:209], v[246:247]
	v_pk_fma_f32 v[244:245], v[162:163], v[206:207], v[244:245]
	global_store_dwordx4 v[192:193], v[244:247], off offset:512
	s_and_b64 vcc, exec, s[2:3]
	s_mov_b64 s[2:3], -1
	s_cbranch_vccnz .LBB0_1496
	s_andn2_b64 vcc, exec, s[6:7]
	s_cbranch_vccnz .LBB0_1495
	s_barrier
	s_branch .LBB0_1495
